# lru_pass: gv DMA before scan + compact constants cache + conv weights cache (no XS prefetch)
# speedup vs baseline: 1.0202x; 1.0012x over previous
; #define LAS __attribute__((address_space(3)))
; __device__ __forceinline__ bf16_t f2bf(float f) { return (bf16_t)(cvt_pk_bf16(f, 0.f) & 0xffffu); }
; __device__ __forceinline__ float bf2f(bf16_t b) { return __uint_as_float(((unsigned)b) << 16); }
; __device__ __forceinline__ void lru_pass(LAS unsigned char* L, int mode, const bf16_t* Z, const bf16_t* LWT, const float* conv_w, const float* conv_b, const float* b_a, const float* b_x, const float* lam,
;                          float* LSUM, const float* LCAR, bf16_t* Y) {
;     ...
;             const int d = tid & 63, ch = n * 64 + d; const float cw0 = conv_w[ch], cw1 = conv_w[512 + ch], cw2 = conv_w[1024 + ch], cw3 = conv_w[1536 + ch], cbv = conv_b[ch];
; #pragma unroll
;             for (int k8 = 0; k8 < 8; ++k8) { const int i = (tid >> 6) + 8 * k8;
;                 const float acc = cbv + bf2f(XS[i * 72 + d]) * cw0 + bf2f(XS[(i + 1) * 72 + d]) * cw1 + bf2f(XS[(i + 2) * 72 + d]) * cw2 + bf2f(XS[(i + 3) * 72 + d]) * cw3;
;                 xc[i * 65 + d] = acc; xcb[i * 72 + d] = f2bf(acc); } }
;         if (n != nprev) { nprev = n;
;         for (int idx = tid; idx < 2048; idx += 512) { const int mat = idx >> 9, d = (idx >> 3) & 63, sg = idx & 7, kind = mat >> 1, g = mat & 1;
;             *(LAS bf16x8*)(LW + mat * 64 * 72 + d * 72 + sg * 8) = *(const bf16x8*)(LWT + (size_t)(kind * 16 + g * 8 + n) * 4096 + d * 64 + sg * 8); } }
.LBB0_599:
	s_or_b64 exec, exec, s[20:21]
	v_or_b32_e32 v48, v46, v41
	v_mov_b32_e32 v49, v0
	v_lshlrev_b64 v[2:3], 2, v[48:49]
	v_lshl_add_u64 v[4:5], s[46:47], 0, v[2:3]
	s_waitcnt lgkmcnt(0)
	s_barrier
	s_cmp_lg_u32 s39, s4
	s_cselect_b32 s98, 0, 1
	s_cmp_lg_u32 s98, 0
	s_cbranch_scc1 .Llru_cw_s0
	global_load_dword v6, v[4:5], off
	global_load_dword v7, v[4:5], off offset:2048
.Llru_cw_s0:
	v_add_co_u32_e32 v4, vcc, 0x1000, v4
	v_lshl_add_u64 v[2:3], s[48:49], 0, v[2:3]
	s_nop 0
	v_addc_co_u32_e32 v5, vcc, 0, v5, vcc
	s_cmp_lg_u32 s98, 0
	s_cbranch_scc1 .Llru_cw_s1
	global_load_dword v8, v[4:5], off
.Llru_cw_s1:
	s_nop 0
	s_cmp_lg_u32 s98, 0
	s_cbranch_scc1 .Llru_cw_s2
	global_load_dword v4, v[4:5], off offset:2048
.Llru_cw_s2:
	ds_read_u16 v5, v58 offset:144
	s_cmp_lg_u32 s98, 0
	s_cbranch_scc1 .Llru_cw_s3
	global_load_dword v2, v[2:3], off
.Llru_cw_s3:
	ds_read_u16 v3, v57
	s_cmp_lg_u32 s39, s4
	s_cselect_b64 s[20:21], -1, 0
	s_waitcnt lgkmcnt(1)
	v_lshlrev_b32_e32 v5, 16, v5
	s_and_b64 s[4:5], s[64:65], s[20:21]
	s_waitcnt lgkmcnt(0)
	v_lshlrev_b32_e32 v3, 16, v3
	s_cmp_lg_u32 s98, 0
	s_cbranch_scc1 .Llru_cw_hit
	s_waitcnt vmcnt(0)
	v_and_b32_e32 v38, 63, v196
	v_lshlrev_b32_e32 v38, 2, v38
	v_add_u32_e32 v38, 0x224b0, v38
	ds_write_b32 v38, v6
	ds_write_b32 v38, v7 offset:256
	ds_write_b32 v38, v8 offset:512
	ds_write_b32 v38, v4 offset:768
	ds_write_b32 v38, v2 offset:1024
	s_branch .Llru_cw_done
.Llru_cw_hit:
	v_and_b32_e32 v38, 63, v196
	v_lshlrev_b32_e32 v38, 2, v38
	v_add_u32_e32 v38, 0x224b0, v38
	ds_read_b32 v6, v38
	ds_read_b32 v7, v38 offset:256
	ds_read_b32 v8, v38 offset:512
	ds_read_b32 v4, v38 offset:768
	ds_read_b32 v2, v38 offset:1024
	s_waitcnt lgkmcnt(0)
.Llru_cw_done:
	v_fma_f32 v3, v6, v3, v2
	v_fmac_f32_e32 v3, v7, v5
	ds_read_u16 v5, v58 offset:288
	s_waitcnt lgkmcnt(0)
	v_lshlrev_b32_e32 v5, 16, v5
	v_fmac_f32_e32 v3, v8, v5
	ds_read_u16 v5, v58 offset:432
	s_waitcnt lgkmcnt(0)
	v_lshlrev_b32_e32 v5, 16, v5
	v_fmac_f32_e32 v3, v4, v5
	ds_write_b32 v245, v3
	v_cvt_pk_bf16_f32 v3, v3, s0
	ds_write_b16 v59, v3 offset:16640
	v_add_u32_e32 v3, 0x480, v57
	ds_read_u16 v3, v3
	ds_read_u16 v5, v60 offset:144
	s_waitcnt lgkmcnt(1)
	v_lshlrev_b32_e32 v3, 16, v3
	v_fma_f32 v3, v6, v3, v2
	s_waitcnt lgkmcnt(0)
	v_lshlrev_b32_e32 v5, 16, v5
	v_fmac_f32_e32 v3, v7, v5
	ds_read_u16 v5, v60 offset:288
	s_waitcnt lgkmcnt(0)
	v_lshlrev_b32_e32 v5, 16, v5
	v_fmac_f32_e32 v3, v8, v5
	ds_read_u16 v5, v60 offset:432
	s_waitcnt lgkmcnt(0)
	v_lshlrev_b32_e32 v5, 16, v5
	v_fmac_f32_e32 v3, v4, v5
	ds_write_b32 v245, v3 offset:2080
	v_cvt_pk_bf16_f32 v3, v3, s0
	ds_write_b16 v59, v3 offset:17792
	v_add_u32_e32 v3, 0x900, v57
	ds_read_u16 v3, v3
	ds_read_u16 v5, v61 offset:144
	s_waitcnt lgkmcnt(1)
	v_lshlrev_b32_e32 v3, 16, v3
	v_fma_f32 v3, v6, v3, v2
	s_waitcnt lgkmcnt(0)
	v_lshlrev_b32_e32 v5, 16, v5
	v_fmac_f32_e32 v3, v7, v5
	ds_read_u16 v5, v61 offset:288
	s_waitcnt lgkmcnt(0)
	v_lshlrev_b32_e32 v5, 16, v5
	v_fmac_f32_e32 v3, v8, v5
	ds_read_u16 v5, v61 offset:432
	s_waitcnt lgkmcnt(0)
	v_lshlrev_b32_e32 v5, 16, v5
	v_fmac_f32_e32 v3, v4, v5
	ds_write_b32 v245, v3 offset:4160
	v_cvt_pk_bf16_f32 v3, v3, s0
	ds_write_b16 v59, v3 offset:18944
	v_add_u32_e32 v3, 0xd80, v57
	ds_read_u16 v3, v3
	ds_read_u16 v5, v62 offset:144
	s_waitcnt lgkmcnt(1)
	v_lshlrev_b32_e32 v3, 16, v3
	v_fma_f32 v3, v6, v3, v2
	s_waitcnt lgkmcnt(0)
	v_lshlrev_b32_e32 v5, 16, v5
	v_fmac_f32_e32 v3, v7, v5
	ds_read_u16 v5, v62 offset:288
	s_waitcnt lgkmcnt(0)
	v_lshlrev_b32_e32 v5, 16, v5
	v_fmac_f32_e32 v3, v8, v5
	ds_read_u16 v5, v62 offset:432
	s_waitcnt lgkmcnt(0)
	v_lshlrev_b32_e32 v5, 16, v5
	v_fmac_f32_e32 v3, v4, v5
	ds_write_b32 v245, v3 offset:6240
	v_cvt_pk_bf16_f32 v3, v3, s0
	ds_write_b16 v59, v3 offset:20096
	v_add_u32_e32 v3, 0x1200, v57
	ds_read_u16 v3, v3
	ds_read_u16 v5, v63 offset:144
	s_waitcnt lgkmcnt(1)
	v_lshlrev_b32_e32 v3, 16, v3
	v_fma_f32 v3, v6, v3, v2
	s_waitcnt lgkmcnt(0)
	v_lshlrev_b32_e32 v5, 16, v5
	v_fmac_f32_e32 v3, v7, v5
	ds_read_u16 v5, v63 offset:288
	s_waitcnt lgkmcnt(0)
	v_lshlrev_b32_e32 v5, 16, v5
	v_fmac_f32_e32 v3, v8, v5
	ds_read_u16 v5, v63 offset:432
	s_waitcnt lgkmcnt(0)
	v_lshlrev_b32_e32 v5, 16, v5
	v_fmac_f32_e32 v3, v4, v5
	ds_write_b32 v245, v3 offset:8320
	v_cvt_pk_bf16_f32 v3, v3, s0
	ds_write_b16 v59, v3 offset:21248
	v_add_u32_e32 v3, 0x1680, v57
	ds_read_u16 v3, v3
	ds_read_u16 v5, v64 offset:144
	s_waitcnt lgkmcnt(1)
	v_lshlrev_b32_e32 v3, 16, v3
	v_fma_f32 v3, v6, v3, v2
	s_waitcnt lgkmcnt(0)
	v_lshlrev_b32_e32 v5, 16, v5
	v_fmac_f32_e32 v3, v7, v5
	ds_read_u16 v5, v64 offset:288
	s_waitcnt lgkmcnt(0)
	v_lshlrev_b32_e32 v5, 16, v5
	v_fmac_f32_e32 v3, v8, v5
	ds_read_u16 v5, v64 offset:432
	s_waitcnt lgkmcnt(0)
	v_lshlrev_b32_e32 v5, 16, v5
	v_fmac_f32_e32 v3, v4, v5
	ds_write_b32 v245, v3 offset:10400
	v_cvt_pk_bf16_f32 v3, v3, s0
	ds_write_b16 v59, v3 offset:22400
	v_add_u32_e32 v3, 0x1b00, v57
	ds_read_u16 v3, v3
	ds_read_u16 v5, v65 offset:144
	s_waitcnt lgkmcnt(1)
	v_lshlrev_b32_e32 v3, 16, v3
	v_fma_f32 v3, v6, v3, v2
	s_waitcnt lgkmcnt(0)
	v_lshlrev_b32_e32 v5, 16, v5
	v_fmac_f32_e32 v3, v7, v5
	ds_read_u16 v5, v65 offset:288
	s_waitcnt lgkmcnt(0)
	v_lshlrev_b32_e32 v5, 16, v5
	v_fmac_f32_e32 v3, v8, v5
	ds_read_u16 v5, v65 offset:432
	s_waitcnt lgkmcnt(0)
	v_lshlrev_b32_e32 v5, 16, v5
	v_fmac_f32_e32 v3, v4, v5
	ds_write_b32 v245, v3 offset:12480
	v_cvt_pk_bf16_f32 v3, v3, s0
	ds_write_b16 v59, v3 offset:23552
	v_add_u32_e32 v3, 0x1f80, v57
	ds_read_u16 v3, v3
	s_waitcnt lgkmcnt(0)
	v_lshlrev_b32_e32 v3, 16, v3
	v_fmac_f32_e32 v2, v6, v3
	ds_read_u16 v3, v248 offset:144
	s_waitcnt lgkmcnt(0)
	v_lshlrev_b32_e32 v3, 16, v3
	v_fmac_f32_e32 v2, v7, v3
	ds_read_u16 v3, v248 offset:288
	s_waitcnt lgkmcnt(0)
	v_lshlrev_b32_e32 v3, 16, v3
	v_fmac_f32_e32 v2, v8, v3
	ds_read_u16 v3, v248 offset:432
	s_waitcnt lgkmcnt(0)
	v_lshlrev_b32_e32 v3, 16, v3
	v_fmac_f32_e32 v2, v4, v3
	ds_write_b32 v245, v2 offset:14560
	v_cvt_pk_bf16_f32 v2, v2, s0
	ds_write_b16 v59, v2 offset:24704
	s_and_saveexec_b64 s[20:21], s[4:5]
	s_cbranch_execz .LBB0_602
	s_mov_b64 s[22:23], 0
	v_mov_b32_e32 v2, v94
	v_mov_b32_e32 v3, v1

; __device__ __forceinline__ void lru_pass(LAS unsigned char* L, int mode, const bf16_t* Z, const bf16_t* LWT, const float* conv_w, const float* conv_b, const float* b_a, const float* b_x, const float* lam,
;                          float* LSUM, const float* LCAR, bf16_t* Y) {
;     ...
;             for (int td = 0; td < 4; ++td) { const int d = td * 16 + fr, ch = n * 64 + d; const float lm = lam[g * 512 + ch]; const float sp = lm > 0.f ? log1pf(expf(-lm)) : -lm + log1pf(expf(lm));
;                 const float ba_ = b_a[g * 512 + ch], bx_ = b_x[g * 512 + ch];
.LBB0_606:
	s_or_b64 exec, exec, s[20:21]
	v_lshrrev_b32_e32 v38, 4, v196
	v_and_b32_e32 v38, 16, v38
	v_and_or_b32 v38, v196, 15, v38
	v_lshlrev_b32_e32 v38, 2, v38
	v_add_u32_e32 v38, 0x21eb0, v38
	ds_write_b32 v38, v54 offset:0
	s_branch .Llru_c0_c
.Llru_c0_b:
	v_lshrrev_b32_e32 v38, 4, v196
	v_and_b32_e32 v38, 16, v38
	v_and_or_b32 v38, v196, 15, v38
	v_lshlrev_b32_e32 v38, 2, v38
	v_add_u32_e32 v38, 0x21eb0, v38
	ds_read_b32 v54, v38 offset:0
	ds_read_b32 v36, v38 offset:128
	ds_read_b32 v37, v38 offset:256
	s_waitcnt lgkmcnt(0)

; __device__ __forceinline__ void lru_pass(LAS unsigned char* L, int mode, const bf16_t* Z, const bf16_t* LWT, const float* conv_w, const float* conv_b, const float* b_a, const float* b_x, const float* lam,
;                          float* LSUM, const float* LCAR, bf16_t* Y) {
;     ...
;             for (int td = 0; td < 4; ++td) { const int d = td * 16 + fr, ch = n * 64 + d; const float lm = lam[g * 512 + ch]; const float sp = lm > 0.f ? log1pf(expf(-lm)) : -lm + log1pf(expf(lm));
;                 const float ba_ = b_a[g * 512 + ch], bx_ = b_x[g * 512 + ch];
.Llru_c0_d1:
	s_mov_b32 s6, 0xc1000000
	s_mov_b32 s3, 0x3e2aaaab
	s_mov_b32 s4, 0xbca3d70a
	v_ashrrev_i32_e32 v51, 31, v50
	s_waitcnt vmcnt(1)
	v_add_f32_e32 v30, v30, v36
	v_mul_f32_e32 v30, 0xbfb8aa3b, v30
	v_exp_f32_e32 v30, v30
	s_waitcnt vmcnt(0)
	s_cmp_lg_u32 s98, 0
	s_cbranch_scc1 .Llru_c0_e
	v_lshrrev_b32_e32 v38, 4, v196
	v_and_b32_e32 v38, 16, v38
	v_and_or_b32 v38, v196, 15, v38
	v_lshlrev_b32_e32 v38, 2, v38
	v_add_u32_e32 v38, 0x21eb0, v38
	ds_write_b32 v38, v36 offset:128
	ds_write_b32 v38, v37 offset:256

; __device__ __forceinline__ void lru_pass(LAS unsigned char* L, int mode, const bf16_t* Z, const bf16_t* LWT, const float* conv_w, const float* conv_b, const float* b_a, const float* b_x, const float* lam,
;                          float* LSUM, const float* LCAR, bf16_t* Y) {
;     ...
;             for (int td = 0; td < 4; ++td) { const int d = td * 16 + fr, ch = n * 64 + d; const float lm = lam[g * 512 + ch]; const float sp = lm > 0.f ? log1pf(expf(-lm)) : -lm + log1pf(expf(lm));
;                 const float ba_ = b_a[g * 512 + ch], bx_ = b_x[g * 512 + ch];
.LBB0_610:
	s_or_b64 exec, exec, s[20:21]
	v_lshrrev_b32_e32 v38, 4, v196
	v_and_b32_e32 v38, 16, v38
	v_and_or_b32 v38, v196, 15, v38
	v_lshlrev_b32_e32 v38, 2, v38
	v_add_u32_e32 v38, 0x21eb0, v38
	ds_write_b32 v38, v32 offset:384
	s_branch .Llru_c1_c
.Llru_c1_b:
	v_lshrrev_b32_e32 v38, 4, v196
	v_and_b32_e32 v38, 16, v38
	v_and_or_b32 v38, v196, 15, v38
	v_lshlrev_b32_e32 v38, 2, v38
	v_add_u32_e32 v38, 0x21eb0, v38
	ds_read_b32 v32, v38 offset:384
	ds_read_b32 v33, v38 offset:512
	ds_read_b32 v36, v38 offset:640
	s_waitcnt lgkmcnt(0)

; __device__ __forceinline__ void lru_pass(LAS unsigned char* L, int mode, const bf16_t* Z, const bf16_t* LWT, const float* conv_w, const float* conv_b, const float* b_a, const float* b_x, const float* lam,
;                          float* LSUM, const float* LCAR, bf16_t* Y) {
;     ...
;             for (int td = 0; td < 4; ++td) { const int d = td * 16 + fr, ch = n * 64 + d; const float lm = lam[g * 512 + ch]; const float sp = lm > 0.f ? log1pf(expf(-lm)) : -lm + log1pf(expf(lm));
;                 const float ba_ = b_a[g * 512 + ch], bx_ = b_x[g * 512 + ch];
.Llru_c1_d1:
	s_mov_b32 s3, 0x3e2aaaab
	s_mov_b32 s4, 0xbca3d70a
	s_waitcnt vmcnt(1)
	v_add_f32_e32 v22, v22, v33
	v_mul_f32_e32 v22, 0xbfb8aa3b, v22
	v_exp_f32_e32 v22, v22
	s_waitcnt vmcnt(0)
	s_cmp_lg_u32 s98, 0
	s_cbranch_scc1 .Llru_c1_e
	v_lshrrev_b32_e32 v38, 4, v196
	v_and_b32_e32 v38, 16, v38
	v_and_or_b32 v38, v196, 15, v38
	v_lshlrev_b32_e32 v38, 2, v38
	v_add_u32_e32 v38, 0x21eb0, v38
	ds_write_b32 v38, v33 offset:512
	ds_write_b32 v38, v36 offset:640

; __device__ __forceinline__ void lru_pass(LAS unsigned char* L, int mode, const bf16_t* Z, const bf16_t* LWT, const float* conv_w, const float* conv_b, const float* b_a, const float* b_x, const float* lam,
;                          float* LSUM, const float* LCAR, bf16_t* Y) {
;     ...
;             for (int td = 0; td < 4; ++td) { const int d = td * 16 + fr, ch = n * 64 + d; const float lm = lam[g * 512 + ch]; const float sp = lm > 0.f ? log1pf(expf(-lm)) : -lm + log1pf(expf(lm));
;                 const float ba_ = b_a[g * 512 + ch], bx_ = b_x[g * 512 + ch];
.LBB0_614:
	s_or_b64 exec, exec, s[20:21]
	v_lshrrev_b32_e32 v38, 4, v196
	v_and_b32_e32 v38, 16, v38
	v_and_or_b32 v38, v196, 15, v38
	v_lshlrev_b32_e32 v38, 2, v38
	v_add_u32_e32 v38, 0x21eb0, v38
	ds_write_b32 v38, v18 offset:768
	s_branch .Llru_c2_c
.Llru_c2_b:
	v_lshrrev_b32_e32 v38, 4, v196
	v_and_b32_e32 v38, 16, v38
	v_and_or_b32 v38, v196, 15, v38
	v_lshlrev_b32_e32 v38, 2, v38
	v_add_u32_e32 v38, 0x21eb0, v38
	ds_read_b32 v18, v38 offset:768
	ds_read_b32 v19, v38 offset:896
	ds_read_b32 v22, v38 offset:1024
	s_waitcnt lgkmcnt(0)

; __device__ __forceinline__ void lru_pass(LAS unsigned char* L, int mode, const bf16_t* Z, const bf16_t* LWT, const float* conv_w, const float* conv_b, const float* b_a, const float* b_x, const float* lam,
;                          float* LSUM, const float* LCAR, bf16_t* Y) {
;     ...
;             for (int td = 0; td < 4; ++td) { const int d = td * 16 + fr, ch = n * 64 + d; const float lm = lam[g * 512 + ch]; const float sp = lm > 0.f ? log1pf(expf(-lm)) : -lm + log1pf(expf(lm));
;                 const float ba_ = b_a[g * 512 + ch], bx_ = b_x[g * 512 + ch];
.Llru_c2_d1:
	s_mov_b32 s3, 0x3e2aaaab
	s_mov_b32 s4, 0xbca3d70a
	s_waitcnt vmcnt(1)
	v_add_f32_e32 v14, v14, v19
	v_mul_f32_e32 v14, 0xbfb8aa3b, v14
	v_exp_f32_e32 v14, v14
	s_waitcnt vmcnt(0)
	s_cmp_lg_u32 s98, 0
	s_cbranch_scc1 .Llru_c2_e
	v_lshrrev_b32_e32 v38, 4, v196
	v_and_b32_e32 v38, 16, v38
	v_and_or_b32 v38, v196, 15, v38
	v_lshlrev_b32_e32 v38, 2, v38
	v_add_u32_e32 v38, 0x21eb0, v38
	ds_write_b32 v38, v19 offset:896
	ds_write_b32 v38, v22 offset:1024

; __device__ __forceinline__ void lru_pass(LAS unsigned char* L, int mode, const bf16_t* Z, const bf16_t* LWT, const float* conv_w, const float* conv_b, const float* b_a, const float* b_x, const float* lam,
;                          float* LSUM, const float* LCAR, bf16_t* Y) {
;     ...
;             for (int td = 0; td < 4; ++td) { const int d = td * 16 + fr, ch = n * 64 + d; const float lm = lam[g * 512 + ch]; const float sp = lm > 0.f ? log1pf(expf(-lm)) : -lm + log1pf(expf(lm));
;                 const float ba_ = b_a[g * 512 + ch], bx_ = b_x[g * 512 + ch];
.LBB0_618:
	s_or_b64 exec, exec, s[20:21]
	v_lshrrev_b32_e32 v38, 4, v196
	v_and_b32_e32 v38, 16, v38
	v_and_or_b32 v38, v196, 15, v38
	v_lshlrev_b32_e32 v38, 2, v38
	v_add_u32_e32 v38, 0x21eb0, v38
	ds_write_b32 v38, v10 offset:1152
	s_branch .Llru_c3_c
.Llru_c3_b:
	v_lshrrev_b32_e32 v38, 4, v196
	v_and_b32_e32 v38, 16, v38
	v_and_or_b32 v38, v196, 15, v38
	v_lshlrev_b32_e32 v38, 2, v38
	v_add_u32_e32 v38, 0x21eb0, v38
	ds_read_b32 v10, v38 offset:1152
	ds_read_b32 v11, v38 offset:1280
	ds_read_b32 v14, v38 offset:1408
	s_waitcnt lgkmcnt(0)

; __device__ __forceinline__ float sigm(float x) { return __builtin_amdgcn_rcpf(1.f + __expf(-x)); }
; __device__ __forceinline__ void lru_pass(LAS unsigned char* L, int mode, const bf16_t* Z, const bf16_t* LWT, const float* conv_w, const float* conv_b, const float* b_a, const float* b_x, const float* lam,
;                          float* LSUM, const float* LCAR, bf16_t* Y) {
;     ...
;             for (int td = 0; td < 4; ++td) { const int d = td * 16 + fr, ch = n * 64 + d; const float lm = lam[g * 512 + ch]; const float sp = lm > 0.f ? log1pf(expf(-lm)) : -lm + log1pf(expf(lm));
;                 const float ba_ = b_a[g * 512 + ch], bx_ = b_x[g * 512 + ch];
; #pragma unroll
;                 for (int r = 0; r < 4; ++r) { const int i = ti * 16 + 4 * fq + r; const float la = -8.f * sigm(aa[td][r] + ba_) * sp;
;                     const float a_ = __expf(la), x2 = 2.f * la; const float om = (x2 > -0.02f) ? -x2 * (1.f + x2 * (0.5f + x2 * (1.f / 6.f))) : 1.f - a_ * a_;
;                     AA[g * 4160 + i * 65 + d] = a_; UU[g * 4160 + i * 65 + d] = __builtin_amdgcn_sqrtf(om) * sigm(ax[td][r] + bx_) * xc[i * 65 + d]; } } }
;         __syncthreads();
;     ...
;             { const int i = tid >> 3, sg = tid & 7; const size_t row = (size_t)b * S_ + seg * 64 + i;
;                 const bf16x8 gv = *(const bf16x8*)(Z + row * 2560 + 2048 + n * 64 + sg * 8); float y[8];
.Llru_c3_d1:
	s_mov_b32 s4, 0xc1000000
	s_mov_b32 s2, 0x3e2aaaab
	s_mov_b32 s3, 0xbca3d70a
	s_waitcnt vmcnt(1)
	v_add_f32_e32 v6, v6, v11
	v_mul_f32_e32 v6, 0xbfb8aa3b, v6
	v_exp_f32_e32 v6, v6
	s_waitcnt vmcnt(0)
	s_cmp_lg_u32 s98, 0
	s_cbranch_scc1 .Llru_c3_e
	v_lshrrev_b32_e32 v38, 4, v196
	v_and_b32_e32 v38, 16, v38
	v_and_or_b32 v38, v196, 15, v38
	v_lshlrev_b32_e32 v38, 2, v38
	v_add_u32_e32 v38, 0x21eb0, v38
	ds_write_b32 v38, v11 offset:1280
	ds_write_b32 v38, v14 offset:1408
.Llru_c3_e:
	v_add_f32_e32 v2, v2, v14
	v_mul_f32_e32 v2, 0xbfb8aa3b, v2
	v_exp_f32_e32 v2, v2
	v_add_f32_e32 v6, 1.0, v6
	v_rcp_f32_e32 v13, v6
	v_add_f32_e32 v6, v7, v11
	v_mul_f32_e32 v6, 0xbfb8aa3b, v6
	v_exp_f32_e32 v6, v6
	v_add_f32_e32 v2, 1.0, v2
	v_rcp_f32_e32 v2, v2
	v_add_f32_e32 v3, v3, v14
	v_add_f32_e32 v6, 1.0, v6
	v_rcp_f32_e32 v12, v6
	v_mul_f32_e32 v3, 0xbfb8aa3b, v3
	v_exp_f32_e32 v3, v3
	v_pk_mul_f32 v[6:7], v[12:13], s[4:5] op_sel_hi:[1,0]
	s_nop 0
	v_pk_mul_f32 v[6:7], v[10:11], v[6:7] op_sel_hi:[0,1]
	v_mul_f32_e32 v12, 0x3fb8aa3b, v7
	v_exp_f32_e32 v15, v12
	v_pk_add_f32 v[12:13], v[6:7], v[6:7]
	v_add_f32_e32 v3, 1.0, v3
	v_fma_f32 v7, v13, s2, 0.5
	v_fma_f32 v7, v13, v7, 1.0
	v_mul_f32_e64 v7, v7, -v13
	v_fma_f32 v16, -v15, v15, 1.0
	v_cmp_lt_f32_e64 s[44:45], s3, v13
	ds_write_b32 v68, v15 offset:62912
	v_cmp_lt_f32_e32 vcc, s3, v12
	v_cndmask_b32_e64 v7, v16, v7, s[44:45]
	v_sqrt_f32_e32 v7, v7
	v_rcp_f32_e32 v3, v3
	v_mul_f32_e32 v2, v2, v7
	ds_read_b32 v7, v69 offset:192
	s_waitcnt lgkmcnt(0)
	v_mul_f32_e32 v2, v7, v2
	ds_write_b32 v84, v2
	v_mul_f32_e32 v2, 0x3fb8aa3b, v6
	v_exp_f32_e32 v2, v2
	v_fma_f32 v6, v12, s2, 0.5
	v_fma_f32 v6, v12, v6, 1.0
	v_mul_f32_e64 v6, v6, -v12
	v_fma_f32 v7, -v2, v2, 1.0
	v_cndmask_b32_e32 v6, v7, v6, vcc
	ds_write_b32 v85, v2 offset:62980
	v_sqrt_f32_e32 v2, v6
	s_nop 0
	v_mul_f32_e32 v2, v3, v2
	ds_read_b32 v3, v69 offset:452
	s_waitcnt lgkmcnt(0)
	v_mul_f32_e32 v2, v3, v2
	ds_write_b32 v86, v2
	v_add_f32_e32 v2, v8, v11
	v_mul_f32_e32 v2, 0xbfb8aa3b, v2
	v_exp_f32_e32 v2, v2
	s_nop 0
	v_add_f32_e32 v2, 1.0, v2
	v_rcp_f32_e32 v3, v2
	v_add_f32_e32 v2, v4, v14
	v_mul_f32_e32 v2, 0xbfb8aa3b, v2
	v_exp_f32_e32 v2, v2
	s_nop 0
	v_add_f32_e32 v2, 1.0, v2
	v_rcp_f32_e32 v4, v2
	v_add_f32_e32 v2, v9, v11
	v_mul_f32_e32 v2, 0xbfb8aa3b, v2
	v_exp_f32_e32 v2, v2
	s_nop 0
	v_add_f32_e32 v2, 1.0, v2
	v_rcp_f32_e32 v2, v2
	s_nop 0
	v_pk_mul_f32 v[2:3], v[2:3], s[4:5] op_sel_hi:[1,0]
	s_nop 0
	v_pk_mul_f32 v[2:3], v[10:11], v[2:3] op_sel_hi:[0,1]
	v_mul_f32_e32 v6, 0x3fb8aa3b, v3
	v_exp_f32_e32 v8, v6
	v_pk_add_f32 v[6:7], v[2:3], v[2:3]
	v_mul_f32_e32 v2, 0x3fb8aa3b, v2
	v_fma_f32 v3, v7, s2, 0.5
	v_fma_f32 v3, v7, v3, 1.0
	v_mul_f32_e64 v3, v3, -v7
	v_fma_f32 v9, -v8, v8, 1.0
	v_cmp_lt_f32_e64 s[44:45], s3, v7
	ds_write_b32 v85, v8 offset:63240
	v_exp_f32_e32 v2, v2
	v_cndmask_b32_e64 v3, v9, v3, s[44:45]
	v_sqrt_f32_e32 v3, v3
	v_cmp_lt_f32_e32 vcc, s3, v6
	v_mul_f32_e32 v3, v4, v3
	ds_read_b32 v4, v69 offset:712
	s_waitcnt lgkmcnt(0)
	v_mul_f32_e32 v3, v4, v3
	ds_write_b32 v87, v3
	v_fma_f32 v3, v6, s2, 0.5
	v_fma_f32 v3, v6, v3, 1.0
	v_mul_f32_e64 v3, v3, -v6
	v_fma_f32 v4, -v2, v2, 1.0
	v_cndmask_b32_e32 v3, v4, v3, vcc
	ds_write_b32 v85, v2 offset:63500
	v_sqrt_f32_e32 v2, v3
	v_add_f32_e32 v3, v5, v14
	v_mul_f32_e32 v3, 0xbfb8aa3b, v3
	v_exp_f32_e32 v3, v3
	s_nop 0
	v_add_f32_e32 v3, 1.0, v3
	v_rcp_f32_e32 v3, v3
	s_nop 0
	v_mul_f32_e32 v2, v3, v2
	ds_read_b32 v3, v69 offset:972
	s_waitcnt lgkmcnt(0)
	v_mul_f32_e32 v2, v3, v2
	ds_write_b32 v88, v2
	s_waitcnt lgkmcnt(0)
	s_barrier
	s_and_b64 vcc, exec, s[60:61]
	s_cbranch_vccz .Llru_gv_skip
	s_ashr_i32 s9, s66, 31
	s_mov_b32 s8, s66
	s_lshl_b64 s[4:5], s[8:9], 14
	s_lshl_b32 s6, s68, 6
	s_or_b32 s4, s4, s6
	v_readlane_b32 s8, v251, 26
	v_readlane_b32 s9, v251, 27
	v_lshl_add_u64 v[6:7], s[4:5], 0, v[92:93]
	s_nop 1
	v_mov_b64_e32 v[2:3], s[8:9]
	v_mad_u64_u32 v[2:3], s[4:5], v6, s10, v[2:3]
	v_mad_i32_i24 v3, v7, s10, v3
	v_mov_b32_e32 v8, v46
	v_mov_b32_e32 v9, v0
	v_lshlrev_b64 v[8:9], 1, v[8:9]
	v_lshl_add_u64 v[2:3], v[2:3], 0, v[8:9]
	v_mov_b32_e32 v8, v44
	v_mov_b32_e32 v9, v0
	v_lshl_add_u64 v[2:3], v[2:3], 0, v[8:9]
	v_add_co_u32_e32 v2, vcc, 0x1000, v2
	s_nop 1
	v_addc_co_u32_e32 v3, vcc, 0, v3, vcc
	v_lshrrev_b32_e32 v4, 6, v196
	s_nop 0
	v_readfirstlane_b32 s4, v4
	s_nop 1
	s_lshl_b32 s4, s4, 10
	s_add_i32 m0, s4, 0x22a00
	s_nop 0
	global_load_lds_dwordx4 v[2:3], off
; __device__ __forceinline__ void lru_pass(LAS unsigned char* L, int mode, const bf16_t* Z, const bf16_t* LWT, const float* conv_w, const float* conv_b, const float* b_a, const float* b_x, const float* lam,
;                          float* LSUM, const float* LCAR, bf16_t* Y) {
;     ...
;         if (tid < 128) { const int g = tid >> 6, d = tid & 63, ch = n * 64 + d; const size_t ix = ((size_t)(b * 256 + seg) * 2 + g) * 512 + ch;
;             if (mode == 0) { float P = 1.f, E = 0.f;
;                 for (int st = 0; st < 64; ++st) { const int i = g ? 63 - st : st; const float a_ = AA[g * 4160 + i * 65 + d]; E = a_ * E + UU[g * 4160 + i * 65 + d]; P *= a_; }
;                 LSUM[2 * ix] = P; LSUM[2 * ix + 1] = E; }
.Llru_gv_skip:
	s_and_saveexec_b64 s[20:21], s[42:43]
	s_cbranch_execz .LBB0_623
	s_lshl_b32 s4, s66, 8
	s_or_b32 s4, s4, s68
	s_ashr_i32 s5, s4, 31
	s_lshl_b64 s[4:5], s[4:5], 10
	v_lshl_add_u64 v[2:3], s[4:5], 0, v[198:199]
	v_lshl_add_u64 v[2:3], v[2:3], 0, v[48:49]
	s_andn2_b64 vcc, exec, s[62:63]
	s_mov_b64 s[22:23], -1
	s_cbranch_vccnz .LBB0_621
	ds_read_b32 v5, v95 offset:62720
	ds_read_b32 v6, v56
	ds_read_b32 v7, v202 offset:62720
	ds_read_b32 v8, v201
	ds_read_b32 v4, v96 offset:62720
	ds_read_b32 v9, v89
	ds_read_b32 v50, v249 offset:62720
	ds_read_b32 v10, v250
	s_waitcnt lgkmcnt(6)
	v_fmac_f32_e32 v6, 0, v5
	s_waitcnt lgkmcnt(4)
	v_fmac_f32_e32 v8, v6, v7
	v_mul_f32_e32 v52, v5, v7
	s_waitcnt lgkmcnt(2)
	v_fmac_f32_e32 v9, v8, v4
	ds_read_b32 v6, v203 offset:62720
	ds_read_b32 v5, v98
	ds_read_b32 v206, v99 offset:62720
	ds_read_b32 v7, v100
	ds_read_b32 v8, v101 offset:62720
	ds_read_b32 v11, v102
	ds_read_b32 v208, v103 offset:62720
	ds_read_b32 v13, v104
	s_waitcnt lgkmcnt(8)
	v_fmac_f32_e32 v10, v9, v50
	s_waitcnt lgkmcnt(6)
	v_fmac_f32_e32 v5, v10, v6
	s_waitcnt lgkmcnt(4)
	v_fmac_f32_e32 v7, v5, v206
	s_waitcnt lgkmcnt(2)
	v_fmac_f32_e32 v11, v7, v8
	ds_read_b32 v12, v105 offset:62720
	ds_read_b32 v5, v106
	ds_read_b32 v210, v107 offset:62720
	ds_read_b32 v7, v108
	ds_read_b32 v16, v109 offset:62720
	ds_read_b32 v9, v110
	ds_read_b32 v212, v111 offset:62720
	ds_read_b32 v10, v112
	s_waitcnt lgkmcnt(8)
	v_fmac_f32_e32 v13, v11, v208
	s_waitcnt lgkmcnt(6)
	v_fmac_f32_e32 v5, v13, v12
	s_waitcnt lgkmcnt(4)
	v_fmac_f32_e32 v7, v5, v210
	s_waitcnt lgkmcnt(2)
	v_fmac_f32_e32 v9, v7, v16
	ds_read_b32 v22, v113 offset:62720
	ds_read_b32 v5, v114
	ds_read_b32 v214, v115 offset:62720
	ds_read_b32 v7, v116
	ds_read_b32 v26, v117 offset:62720
	ds_read_b32 v11, v118
	ds_read_b32 v216, v119 offset:62720
	ds_read_b32 v13, v120
	s_waitcnt lgkmcnt(8)
	v_fmac_f32_e32 v10, v9, v212
	s_waitcnt lgkmcnt(6)
	v_fmac_f32_e32 v5, v10, v22
	s_waitcnt lgkmcnt(4)
	v_fmac_f32_e32 v7, v5, v214
	s_waitcnt lgkmcnt(2)
	v_fmac_f32_e32 v11, v7, v26
	ds_read_b32 v30, v121 offset:62720
	ds_read_b32 v5, v122
	ds_read_b32 v218, v123 offset:62720
	ds_read_b32 v7, v124
	ds_read_b32 v10, v125 offset:62720
	ds_read_b32 v9, v126
	s_waitcnt lgkmcnt(6)
	v_fmac_f32_e32 v13, v11, v216
	v_mov_b32_e32 v21, v220
	ds_read_b32 v220, v127 offset:62720
	ds_read_b32 v11, v128
	s_waitcnt lgkmcnt(6)
	v_fmac_f32_e32 v5, v13, v30
	s_waitcnt lgkmcnt(4)
	v_fmac_f32_e32 v7, v5, v218
	s_waitcnt lgkmcnt(2)
	v_fmac_f32_e32 v9, v7, v10
	ds_read_b32 v14, v129 offset:62720
	ds_read_b32 v5, v130
	ds_read_b32 v204, v131 offset:62720
	ds_read_b32 v7, v132
	ds_read_b32 v18, v133 offset:62720
	ds_read_b32 v13, v134
	s_waitcnt lgkmcnt(6)
	v_fmac_f32_e32 v11, v9, v220
	v_mov_b32_e32 v45, v94
	v_mov_b32_e32 v47, v95
	v_mov_b64_e32 v[94:95], v[92:93]
	v_mov_b64_e32 v[92:93], v[198:199]
	ds_read_b32 v198, v135 offset:62720
	ds_read_b32 v15, v136
	s_waitcnt lgkmcnt(6)
	v_fmac_f32_e32 v5, v11, v14
	s_waitcnt lgkmcnt(4)
	v_fmac_f32_e32 v7, v5, v204
	ds_read_b32 v20, v137 offset:62720
	ds_read_b32 v5, v138
	s_waitcnt lgkmcnt(4)
	v_fmac_f32_e32 v13, v7, v18
	v_mov_b32_e32 v54, v202
	ds_read_b32 v202, v139 offset:62720
	ds_read_b32 v7, v140
	ds_read_b32 v24, v141 offset:62720
	ds_read_b32 v9, v142
	ds_read_b32 v36, v143 offset:62720
	ds_read_b32 v11, v144
	s_waitcnt lgkmcnt(8)
	v_fmac_f32_e32 v15, v13, v198
	s_waitcnt lgkmcnt(6)
	v_fmac_f32_e32 v5, v15, v20
	s_waitcnt lgkmcnt(4)
	v_fmac_f32_e32 v7, v5, v202
	s_waitcnt lgkmcnt(2)
	v_fmac_f32_e32 v9, v7, v24
	ds_read_b32 v28, v145 offset:62720
	ds_read_b32 v5, v146
	ds_read_b32 v42, v147 offset:62720
	ds_read_b32 v7, v148
	ds_read_b32 v32, v149 offset:62720
	ds_read_b32 v13, v150
	ds_read_b32 v38, v151 offset:62720
	ds_read_b32 v15, v152
	s_waitcnt lgkmcnt(8)
	v_fmac_f32_e32 v11, v9, v36
	s_waitcnt lgkmcnt(6)
	v_fmac_f32_e32 v5, v11, v28
	s_waitcnt lgkmcnt(4)
	v_fmac_f32_e32 v7, v5, v42
	s_waitcnt lgkmcnt(2)
	v_fmac_f32_e32 v13, v7, v32
	s_waitcnt lgkmcnt(0)
	v_fmac_f32_e32 v15, v13, v38
	ds_read_b32 v48, v153 offset:62720
	ds_read_b32 v53, v156
	ds_read_b32 v5, v157 offset:62720
	ds_read_b32 v51, v158
	ds_read_b32 v7, v159 offset:62720
	ds_read_b32 v207, v160
	ds_read_b32 v9, v161 offset:62720
	ds_read_b32 v209, v162
	s_waitcnt lgkmcnt(6)
	v_fmac_f32_e32 v53, v15, v48
	v_mul_f32_e32 v11, v52, v4
	v_mov_b32_e32 v155, v96
	v_mov_b64_e32 v[96:97], v[90:91]
	v_mul_f32_e32 v90, v11, v50
	s_waitcnt lgkmcnt(4)
	v_pk_fma_f32 v[50:51], v[52:53], v[4:5], v[50:51]
	ds_read_b32 v13, v163 offset:62720
	ds_read_b32 v211, v164
	ds_read_b32 v17, v165 offset:62720
	ds_read_b32 v213, v166
	ds_read_b32 v23, v167 offset:62720
	ds_read_b32 v215, v168
	ds_read_b32 v27, v169 offset:62720
	ds_read_b32 v217, v170
	v_mov_b32_e32 v91, v51
	s_waitcnt lgkmcnt(11)
	v_pk_mul_f32 v[50:51], v[90:91], v[6:7]
	s_waitcnt lgkmcnt(10)
	v_pk_fma_f32 v[52:53], v[90:91], v[6:7], v[206:207]
	v_pk_mul_f32 v[50:51], v[50:51], v[206:207]
	ds_read_b32 v31, v171 offset:62720
	ds_read_b32 v219, v172
	ds_read_b32 v11, v173 offset:62720
	ds_read_b32 v221, v174
	ds_read_b32 v15, v175 offset:62720
	ds_read_b32 v205, v176
	ds_read_b32 v19, v177 offset:62720
	ds_read_b32 v199, v178
	v_mov_b32_e32 v52, v50
	s_waitcnt lgkmcnt(14)
	v_pk_mul_f32 v[50:51], v[50:51], v[8:9]
	v_pk_fma_f32 v[52:53], v[52:53], v[8:9], v[208:209]
	v_pk_mul_f32 v[50:51], v[50:51], v[208:209]
	v_mov_b32_e32 v4, v5
	v_mov_b32_e32 v51, v53
	v_pk_mul_f32 v[52:53], v[50:51], v[12:13]
	v_pk_fma_f32 v[50:51], v[50:51], v[12:13], v[210:211]
	v_pk_mul_f32 v[52:53], v[52:53], v[210:211]
	v_mov_b32_e32 v6, v7
	v_mov_b32_e32 v50, v52
	s_waitcnt lgkmcnt(13)
; __device__ __forceinline__ void lru_pass(LAS unsigned char* L, int mode, const bf16_t* Z, const bf16_t* LWT, const float* conv_w, const float* conv_b, const float* b_a, const float* b_x, const float* lam,
;                          float* LSUM, const float* LCAR, bf16_t* Y) {
;     ...
;             if (mode == 0) { float P = 1.f, E = 0.f;
;                 for (int st = 0; st < 64; ++st) { const int i = g ? 63 - st : st; const float a_ = AA[g * 4160 + i * 65 + d]; E = a_ * E + UU[g * 4160 + i * 65 + d]; P *= a_; }
;                 LSUM[2 * ix] = P; LSUM[2 * ix + 1] = E; }
	v_pk_mul_f32 v[52:53], v[52:53], v[16:17]
	s_waitcnt lgkmcnt(12)
	v_pk_fma_f32 v[50:51], v[50:51], v[16:17], v[212:213]
	v_pk_mul_f32 v[52:53], v[52:53], v[212:213]
	v_mov_b32_e32 v8, v17
	v_mov_b32_e32 v53, v51
	s_waitcnt lgkmcnt(11)
	v_pk_mul_f32 v[50:51], v[52:53], v[22:23]
	s_waitcnt lgkmcnt(10)
	v_pk_fma_f32 v[52:53], v[52:53], v[22:23], v[214:215]
	v_pk_mul_f32 v[50:51], v[50:51], v[214:215]
	v_mov_b32_e32 v90, v17
	v_mov_b32_e32 v52, v50
	s_waitcnt lgkmcnt(9)
	v_pk_mul_f32 v[50:51], v[50:51], v[26:27]
	s_waitcnt lgkmcnt(8)
	v_pk_fma_f32 v[52:53], v[52:53], v[26:27], v[216:217]
	v_pk_mul_f32 v[50:51], v[50:51], v[216:217]
	s_waitcnt lgkmcnt(3)
	v_mov_b32_e32 v12, v15
	v_mov_b32_e32 v51, v53
	v_pk_mul_f32 v[52:53], v[50:51], v[30:31]
	v_pk_fma_f32 v[50:51], v[50:51], v[30:31], v[218:219]
	v_pk_mul_f32 v[52:53], v[52:53], v[218:219]
	s_waitcnt lgkmcnt(1)
	v_mov_b32_e32 v16, v19
	v_mov_b32_e32 v50, v52
	v_pk_mul_f32 v[52:53], v[52:53], v[10:11]
	v_pk_fma_f32 v[50:51], v[50:51], v[10:11], v[220:221]
	v_pk_mul_f32 v[52:53], v[52:53], v[220:221]
	v_mov_b32_e32 v220, v21
	v_mov_b32_e32 v53, v51
	v_pk_mul_f32 v[50:51], v[52:53], v[14:15]
	ds_read_b32 v21, v179 offset:62720
	v_pk_mul_f32 v[50:51], v[50:51], v[204:205]
	v_pk_fma_f32 v[52:53], v[52:53], v[14:15], v[204:205]
	v_mov_b32_e32 v10, v203
	v_mov_b32_e32 v52, v50
	v_pk_mul_f32 v[50:51], v[50:51], v[18:19]
	s_waitcnt lgkmcnt(1)
	v_pk_fma_f32 v[52:53], v[52:53], v[18:19], v[198:199]
	v_pk_mul_f32 v[50:51], v[50:51], v[198:199]
	ds_read_b32 v203, v180
	ds_read_b32 v25, v181 offset:62720
	ds_read_b32 v37, v182
	ds_read_b32 v29, v183 offset:62720
	ds_read_b32 v43, v184
	ds_read_b32 v33, v185 offset:62720
	ds_read_b32 v39, v186
	v_mov_b32_e32 v51, v53
	s_waitcnt lgkmcnt(7)
	v_pk_mul_f32 v[52:53], v[50:51], v[20:21]
	s_waitcnt lgkmcnt(6)
	v_pk_fma_f32 v[50:51], v[50:51], v[20:21], v[202:203]
	v_pk_mul_f32 v[52:53], v[52:53], v[202:203]
	v_mov_b32_e32 v198, v23
	v_mov_b32_e32 v50, v52
	s_waitcnt lgkmcnt(5)
	v_pk_mul_f32 v[52:53], v[52:53], v[24:25]
	v_mov_b32_e32 v202, v27
	s_waitcnt lgkmcnt(4)
	v_pk_mul_f32 v[52:53], v[52:53], v[36:37]
	v_pk_fma_f32 v[36:37], v[50:51], v[24:25], v[36:37]
	v_mov_b32_e32 v50, v9
	v_mov_b32_e32 v53, v37
	s_waitcnt lgkmcnt(3)
	v_pk_mul_f32 v[36:37], v[52:53], v[28:29]
	v_mov_b32_e32 v22, v21
	s_waitcnt lgkmcnt(2)
	v_pk_mul_f32 v[36:37], v[36:37], v[42:43]
	v_pk_fma_f32 v[42:43], v[52:53], v[28:29], v[42:43]
	v_mov_b32_e32 v52, v13
	v_mov_b32_e32 v42, v36
	s_waitcnt lgkmcnt(1)
	v_pk_mul_f32 v[36:37], v[36:37], v[32:33]
	v_mov_b32_e32 v26, v25
	s_waitcnt lgkmcnt(0)
	v_pk_mul_f32 v[36:37], v[36:37], v[38:39]
	v_pk_fma_f32 v[38:39], v[42:43], v[32:33], v[38:39]
	v_mov_b32_e32 v42, v7
	v_mov_b32_e32 v37, v39
	ds_read_b32 v49, v187 offset:62720
	ds_read_b32 v39, v188
	ds_read_b32 v43, v189 offset:62720
	ds_read_b32 v51, v190
	ds_read_b32 v53, v191 offset:62720
	ds_read_b32 v91, v192
	ds_read_b32 v199, v193 offset:62720
	ds_read_b32 v203, v194
	s_waitcnt lgkmcnt(7)
	v_pk_mul_f32 v[204:205], v[36:37], v[48:49]
	v_mov_b32_e32 v38, v5
	v_pk_mul_f32 v[4:5], v[204:205], v[4:5]
	s_waitcnt lgkmcnt(6)
	v_pk_fma_f32 v[36:37], v[36:37], v[48:49], v[38:39]
	v_mov_b32_e32 v30, v29
	v_mov_b32_e32 v36, v4
	v_pk_mul_f32 v[4:5], v[4:5], v[6:7]
	v_mov_b32_e32 v6, v9
	v_pk_mul_f32 v[4:5], v[4:5], v[6:7]
	s_waitcnt lgkmcnt(4)
	v_pk_fma_f32 v[6:7], v[36:37], v[42:43], v[50:51]
	v_mov_b32_e32 v36, v33
	v_mov_b32_e32 v5, v7
	s_waitcnt lgkmcnt(3)
	v_pk_mul_f32 v[6:7], v[4:5], v[52:53]
	s_waitcnt lgkmcnt(2)
	v_pk_fma_f32 v[4:5], v[4:5], v[52:53], v[90:91]
	v_pk_mul_f32 v[6:7], v[6:7], v[8:9]
	v_mov_b32_e32 v8, v23
	v_mov_b32_e32 v4, v6
	v_pk_mul_f32 v[6:7], v[6:7], v[8:9]
	v_mov_b32_e32 v8, v27
	v_pk_mul_f32 v[6:7], v[6:7], v[8:9]
	s_waitcnt lgkmcnt(0)
	v_pk_fma_f32 v[4:5], v[4:5], v[198:199], v[202:203]
	v_mov_b32_e32 v203, v10
	v_mov_b32_e32 v7, v5
	v_mov_b32_e32 v4, v31
	ds_read_b32 v5, v195 offset:62720
	ds_read_b32 v9, v223
	ds_read_b32 v13, v224 offset:62720
	ds_read_b32 v17, v225
	ds_read_b32 v23, v226 offset:62720
	ds_read_b32 v27, v227
	ds_read_b32 v31, v228 offset:62720
	ds_read_b32 v37, v229
	s_waitcnt lgkmcnt(7)
; __device__ __forceinline__ void lru_pass(LAS unsigned char* L, int mode, const bf16_t* Z, const bf16_t* LWT, const float* conv_w, const float* conv_b, const float* b_a, const float* b_x, const float* lam,
;                          float* LSUM, const float* LCAR, bf16_t* Y) {
;     ...
;             if (mode == 0) { float P = 1.f, E = 0.f;
;                 for (int st = 0; st < 64; ++st) { const int i = g ? 63 - st : st; const float a_ = AA[g * 4160 + i * 65 + d]; E = a_ * E + UU[g * 4160 + i * 65 + d]; P *= a_; }
;                 LSUM[2 * ix] = P; LSUM[2 * ix + 1] = E; }
	v_pk_mul_f32 v[38:39], v[6:7], v[4:5]
	v_mov_b32_e32 v10, v11
	v_mov_b32_e32 v8, v11
	v_pk_mul_f32 v[10:11], v[38:39], v[10:11]
	s_waitcnt lgkmcnt(6)
	v_pk_fma_f32 v[6:7], v[6:7], v[4:5], v[8:9]
	v_mov_b32_e32 v4, v15
	v_mov_b32_e32 v6, v10
	v_pk_mul_f32 v[8:9], v[10:11], v[4:5]
	v_mov_b32_e32 v4, v19
	v_pk_mul_f32 v[8:9], v[8:9], v[4:5]
	s_waitcnt lgkmcnt(4)
	v_pk_fma_f32 v[6:7], v[6:7], v[12:13], v[16:17]
	v_mov_b32_e32 v4, v25
	v_mov_b32_e32 v9, v7
	s_waitcnt lgkmcnt(3)
	v_pk_mul_f32 v[6:7], v[8:9], v[22:23]
	s_waitcnt lgkmcnt(2)
	v_pk_fma_f32 v[8:9], v[8:9], v[22:23], v[26:27]
	v_pk_mul_f32 v[6:7], v[6:7], v[4:5]
	v_mov_b32_e32 v4, v29
	v_mov_b32_e32 v8, v6
	v_pk_mul_f32 v[6:7], v[6:7], v[4:5]
	v_mov_b32_e32 v4, v33
	v_pk_mul_f32 v[6:7], v[6:7], v[4:5]
	s_waitcnt lgkmcnt(0)
	v_pk_fma_f32 v[8:9], v[8:9], v[30:31], v[36:37]
	v_mov_b32_e32 v4, v43
	v_mov_b32_e32 v7, v9
	v_mov_b32_e32 v8, v49
	ds_read_b32 v9, v230 offset:62720
	ds_read_b32 v11, v231
	ds_read_b32 v15, v232 offset:62720
	ds_read_b32 v17, v233
	ds_read_b32 v19, v234 offset:62720
	ds_read_b32 v21, v235
	ds_read_b32 v25, v236 offset:62720
	ds_read_b32 v27, v237
	s_waitcnt lgkmcnt(7)
	v_pk_mul_f32 v[28:29], v[6:7], v[8:9]
	v_mov_b32_e32 v10, v43
	v_pk_mul_f32 v[28:29], v[28:29], v[4:5]
	s_waitcnt lgkmcnt(6)
	v_pk_fma_f32 v[6:7], v[6:7], v[8:9], v[10:11]
	v_mov_b32_e32 v4, v53
	v_mov_b32_e32 v6, v28
	v_mov_b32_e32 v14, v53
	v_pk_mul_f32 v[10:11], v[28:29], v[4:5]
	v_mov_b32_e32 v4, v199
	v_mov_b32_e32 v16, v199
	v_pk_mul_f32 v[10:11], v[10:11], v[4:5]
	s_waitcnt lgkmcnt(4)
	v_pk_fma_f32 v[6:7], v[6:7], v[14:15], v[16:17]
	v_mov_b32_e32 v18, v5
	v_mov_b32_e32 v11, v7
	s_waitcnt lgkmcnt(3)
	v_pk_mul_f32 v[4:5], v[10:11], v[18:19]
	v_mov_b32_e32 v6, v13
	v_mov_b32_e32 v20, v13
	v_pk_mul_f32 v[4:5], v[4:5], v[6:7]
	s_waitcnt lgkmcnt(2)
	v_pk_fma_f32 v[6:7], v[10:11], v[18:19], v[20:21]
	v_mov_b32_e32 v8, v23
	v_mov_b32_e32 v6, v4
	v_mov_b32_e32 v24, v23
	v_pk_mul_f32 v[4:5], v[4:5], v[8:9]
	v_mov_b32_e32 v8, v31
	v_mov_b32_e32 v26, v31
	v_pk_mul_f32 v[4:5], v[4:5], v[8:9]
	s_waitcnt lgkmcnt(0)
	v_pk_fma_f32 v[6:7], v[6:7], v[24:25], v[26:27]
	v_mov_b32_e32 v10, v9
	v_mov_b32_e32 v5, v7
	ds_read_b32 v11, v238 offset:62720
	ds_read_b32 v13, v239
	ds_read_b32 v17, v240 offset:62720
	ds_read_b32 v21, v241
	ds_read_b32 v29, v243 offset:62720
	ds_read_b32 v33, v244
	ds_read_b32 v37, v246 offset:62720
	ds_read_b32 v39, v247
	s_waitcnt lgkmcnt(7)
	v_pk_mul_f32 v[6:7], v[4:5], v[10:11]
	v_mov_b32_e32 v8, v15
	v_mov_b32_e32 v12, v15
	v_pk_mul_f32 v[6:7], v[6:7], v[8:9]
	s_waitcnt lgkmcnt(6)
	v_pk_fma_f32 v[4:5], v[4:5], v[10:11], v[12:13]
	v_mov_b32_e32 v8, v19
	v_mov_b32_e32 v4, v6
	v_mov_b32_e32 v16, v19
	v_pk_mul_f32 v[6:7], v[6:7], v[8:9]
	v_mov_b32_e32 v8, v25
	v_mov_b32_e32 v20, v25
	v_pk_mul_f32 v[6:7], v[6:7], v[8:9]
	s_waitcnt lgkmcnt(4)
	v_pk_fma_f32 v[4:5], v[4:5], v[16:17], v[20:21]
	v_mov_b32_e32 v28, v11
	v_mov_b32_e32 v7, v5
	s_waitcnt lgkmcnt(3)
	v_pk_mul_f32 v[4:5], v[6:7], v[28:29]
	v_mov_b32_e32 v8, v17
	v_mov_b32_e32 v32, v17
	v_pk_mul_f32 v[4:5], v[4:5], v[8:9]
	s_waitcnt lgkmcnt(2)
	v_pk_fma_f32 v[6:7], v[6:7], v[28:29], v[32:33]
	v_mov_b32_e32 v8, v29
	v_mov_b32_e32 v6, v4
	v_mov_b32_e32 v36, v29
	v_pk_mul_f32 v[4:5], v[4:5], v[8:9]
	s_waitcnt lgkmcnt(1)
	v_mov_b32_e32 v8, v37
	v_mov_b32_e32 v38, v37
	v_pk_mul_f32 v[4:5], v[4:5], v[8:9]
	s_waitcnt lgkmcnt(0)
	v_pk_fma_f32 v[6:7], v[6:7], v[36:37], v[38:39]
	v_mov_b64_e32 v[90:91], v[96:97]
	v_mov_b32_e32 v96, v155
	v_mov_b32_e32 v202, v54
	v_mov_b64_e32 v[198:199], v[92:93]
	v_mov_b64_e32 v[92:93], v[94:95]
	v_mov_b32_e32 v95, v47
	v_mov_b32_e32 v94, v45
	v_lshl_add_u64 v[42:43], v[2:3], 3, s[30:31]
	v_mov_b32_e32 v5, v7
	s_mov_b64 s[22:23], 0
	global_store_dwordx2 v[42:43], v[4:5], off

; __device__ __forceinline__ unsigned cvt_pk_bf16(float lo, float hi) { const f32x2_t v = {lo, hi}; const bf16x2_t b = __builtin_convertvector(v, bf16x2_t); return __builtin_bit_cast(unsigned, b); }
; __device__ __forceinline__ float bfs2f(short b) { return __uint_as_float(((unsigned)(unsigned short)b) << 16); }
; __device__ __forceinline__ float gelu_tanh(float x) { return 0.5f * x * (1.f + tanh_fast(0.7978845608f * (x + 0.044715f * x * x * x))); }
; __device__ __forceinline__ void lru_pass(LAS unsigned char* L, int mode, const bf16_t* Z, const bf16_t* LWT, const float* conv_w, const float* conv_b, const float* b_a, const float* b_x, const float* lam,
;                          float* LSUM, const float* LCAR, bf16_t* Y) {
;     ...
;         if (mode == 1) {
;             { const int i = tid >> 3, sg = tid & 7; const size_t row = (size_t)b * S_ + seg * 64 + i;
;                 const bf16x8 gv = *(const bf16x8*)(Z + row * 2560 + 2048 + n * 64 + sg * 8); float y[8];
; #pragma unroll
;                 for (int e = 0; e < 8; ++e) { const int d = sg * 8 + e; y[e] = (UU[i * 65 + d] + UU[4160 + i * 65 + d]) * gelu_tanh(bfs2f(gv[e])); }
;                 u32x4 w; w.x = cvt_pk_bf16(y[0], y[1]); w.y = cvt_pk_bf16(y[2], y[3]); w.z = cvt_pk_bf16(y[4], y[5]); w.w = cvt_pk_bf16(y[6], y[7]);
;                 *(u32x4*)(Y + row * 1024 + 512 + n * 64 + sg * 8) = w; }
.LBB0_623:
	s_or_b64 exec, exec, s[20:21]
	s_andn2_b64 vcc, exec, s[60:61]
	s_waitcnt lgkmcnt(0)
	s_barrier
	s_cbranch_vccnz .LBB0_590
	s_ashr_i32 s67, s66, 31
	s_lshl_b64 s[4:5], s[66:67], 14
	s_lshl_b32 s6, s68, 6
	v_readlane_b32 s2, v251, 26
	s_or_b32 s4, s4, s6
	v_readlane_b32 s3, v251, 27
	v_lshl_add_u64 v[6:7], s[4:5], 0, v[92:93]
	v_mov_b32_e32 v47, v0
	v_mov_b64_e32 v[2:3], s[2:3]
	v_mad_u64_u32 v[2:3], s[4:5], v6, s10, v[2:3]
	v_mad_i32_i24 v3, v7, s10, v3
	v_lshlrev_b64 v[8:9], 1, v[46:47]
	v_lshl_add_u64 v[2:3], v[2:3], 0, v[8:9]
	v_mov_b32_e32 v45, v0
	v_lshl_add_u64 v[2:3], v[2:3], 0, v[44:45]
	s_movk_i32 s2, 0x1000
	v_add_co_u32_e32 v2, vcc, s2, v2
	ds_read2_b32 v[14:15], v242 offset1:1
	s_nop 0
	v_addc_co_u32_e32 v3, vcc, 0, v3, vcc
	s_waitcnt vmcnt(0)
	v_lshlrev_b32_e32 v2, 4, v196
	v_add_u32_e32 v2, 0x22a00, v2
	ds_read_b128 v[2:5], v2
	v_readlane_b32 s2, v251, 22
	v_readlane_b32 s3, v251, 23
	s_waitcnt lgkmcnt(0)
	v_lshlrev_b32_e32 v10, 16, v2
	v_and_b32_e32 v11, 0xffff0000, v2
	v_mul_f32_e32 v2, 0x3d372713, v10
	v_mul_f32_e32 v2, v2, v10
	v_mov_b32_e32 v12, v10
	v_fmac_f32_e32 v12, v2, v12
	v_mul_f32_e32 v2, 0x3f4c422a, v12
	v_add_f32_e32 v2, v2, v2
	v_mul_f32_e32 v2, 0x3fb8aa3b, v2
	v_exp_f32_e32 v12, v2
	v_add_u32_e32 v2, 0x4100, v242
	ds_read2_b32 v[16:17], v2 offset1:1
	v_mul_f32_e32 v2, 0x3d372713, v11
	v_mul_f32_e32 v2, v2, v11
	s_waitcnt lgkmcnt(0)
	v_pk_add_f32 v[14:15], v[14:15], v[16:17]
	v_pk_mul_f32 v[16:17], v[10:11], 0.5 op_sel_hi:[1,0]
	v_fmac_f32_e32 v11, v2, v11
	v_mul_f32_e32 v2, 0x3f4c422a, v11
	v_add_f32_e32 v2, v2, v2
	v_mul_f32_e32 v2, 0x3fb8aa3b, v2
	v_exp_f32_e32 v13, v2
	s_nop 0
	v_pk_add_f32 v[10:11], v[12:13], 1.0 op_sel_hi:[1,0]
	s_nop 0
	v_div_scale_f32 v2, s[4:5], v11, v11, 2.0
	v_rcp_f32_e32 v12, v2
	s_nop 0
	v_fma_f32 v13, -v2, v12, 1.0
	v_fmac_f32_e32 v12, v13, v12
	v_div_scale_f32 v13, vcc, 2.0, v11, 2.0
	v_mul_f32_e32 v18, v13, v12
	v_fma_f32 v19, -v2, v18, v13
	v_fmac_f32_e32 v18, v19, v12
	v_fma_f32 v2, -v2, v18, v13
	v_div_fmas_f32 v2, v2, v12, v18
	v_div_fixup_f32 v11, v2, v11, 2.0
	v_div_scale_f32 v2, s[4:5], v10, v10, 2.0
	v_rcp_f32_e32 v12, v2
	s_nop 0
	v_fma_f32 v13, -v2, v12, 1.0
	v_fmac_f32_e32 v12, v13, v12
	v_div_scale_f32 v13, vcc, 2.0, v10, 2.0
	v_mul_f32_e32 v18, v13, v12
	v_fma_f32 v19, -v2, v18, v13
	v_fmac_f32_e32 v18, v19, v12
	v_fma_f32 v2, -v2, v18, v13
	v_div_fmas_f32 v2, v2, v12, v18
	v_lshlrev_b32_e32 v12, 16, v3
	v_div_fixup_f32 v10, v2, v10, 2.0
	v_mul_f32_e32 v2, 0x3d372713, v12
	v_pk_add_f32 v[10:11], v[10:11], 1.0 op_sel_hi:[1,0] neg_lo:[1,0] neg_hi:[1,0]
	v_and_b32_e32 v13, 0xffff0000, v3
	v_mul_f32_e32 v2, v2, v12
	v_mov_b32_e32 v3, v12
	v_pk_add_f32 v[10:11], v[10:11], 1.0 op_sel_hi:[1,0]
	v_fmac_f32_e32 v3, v2, v3
	v_pk_mul_f32 v[10:11], v[16:17], v[10:11]
	v_mul_f32_e32 v2, 0x3f4c422a, v3
	v_add_u32_e32 v3, 0x4108, v242
	v_pk_mul_f32 v[10:11], v[14:15], v[10:11]
	ds_read2_b32 v[14:15], v242 offset0:2 offset1:3
	ds_read2_b32 v[16:17], v3 offset1:1
	v_mul_f32_e32 v3, 0x3d372713, v13
	v_mul_f32_e32 v3, v3, v13
	v_add_f32_e32 v2, v2, v2
	v_mul_f32_e32 v2, 0x3fb8aa3b, v2
	s_waitcnt lgkmcnt(0)
	v_pk_add_f32 v[14:15], v[14:15], v[16:17]
	v_pk_mul_f32 v[16:17], v[12:13], 0.5 op_sel_hi:[1,0]
	v_fmac_f32_e32 v13, v3, v13
	v_mul_f32_e32 v3, 0x3f4c422a, v13
	v_add_f32_e32 v3, v3, v3
	v_mul_f32_e32 v3, 0x3fb8aa3b, v3
	v_exp_f32_e32 v2, v2
	v_exp_f32_e32 v3, v3
	v_cvt_pk_bf16_f32 v10, v10, v11
	v_pk_add_f32 v[2:3], v[2:3], 1.0 op_sel_hi:[1,0]
	s_nop 0
	v_div_scale_f32 v12, s[4:5], v3, v3, 2.0
	v_rcp_f32_e32 v13, v12
	s_nop 0
	v_fma_f32 v18, -v12, v13, 1.0
	v_fmac_f32_e32 v13, v18, v13
	v_div_scale_f32 v18, vcc, 2.0, v3, 2.0
	v_mul_f32_e32 v19, v18, v13
	v_fma_f32 v20, -v12, v19, v18
	v_fmac_f32_e32 v19, v20, v13
	v_fma_f32 v12, -v12, v19, v18
	v_div_fmas_f32 v12, v12, v13, v19
	v_div_fixup_f32 v3, v12, v3, 2.0
	v_div_scale_f32 v12, s[4:5], v2, v2, 2.0
	v_rcp_f32_e32 v13, v12
	s_nop 0
	v_fma_f32 v18, -v12, v13, 1.0
	v_fmac_f32_e32 v13, v18, v13
	v_div_scale_f32 v18, vcc, 2.0, v2, 2.0
	v_mul_f32_e32 v19, v18, v13
	v_fma_f32 v20, -v12, v19, v18
	v_fmac_f32_e32 v19, v20, v13
	v_fma_f32 v12, -v12, v19, v18
	v_div_fmas_f32 v12, v12, v13, v19
	v_div_fixup_f32 v2, v12, v2, 2.0
	v_pk_add_f32 v[2:3], v[2:3], 1.0 op_sel_hi:[1,0] neg_lo:[1,0] neg_hi:[1,0]
	v_lshlrev_b32_e32 v12, 16, v4
	v_pk_add_f32 v[2:3], v[2:3], 1.0 op_sel_hi:[1,0]
	v_and_b32_e32 v13, 0xffff0000, v4
	v_pk_mul_f32 v[2:3], v[16:17], v[2:3]
	v_mul_f32_e32 v4, 0x3d372713, v12
	v_pk_mul_f32 v[2:3], v[14:15], v[2:3]
	v_mul_f32_e32 v4, v4, v12
	v_mov_b32_e32 v14, v12
	v_fmac_f32_e32 v14, v4, v14
	v_mul_f32_e32 v4, 0x3f4c422a, v14
	v_add_f32_e32 v4, v4, v4
	v_mul_f32_e32 v4, 0x3fb8aa3b, v4
	v_exp_f32_e32 v14, v4
	v_add_u32_e32 v4, 0x4110, v242
	ds_read2_b32 v[16:17], v242 offset0:4 offset1:5
	ds_read2_b32 v[18:19], v4 offset1:1
	v_mul_f32_e32 v4, 0x3d372713, v13
	v_mul_f32_e32 v4, v4, v13
	v_cvt_pk_bf16_f32 v11, v2, v3
	v_lshlrev_b64 v[2:3], 11, v[6:7]
	s_waitcnt lgkmcnt(0)
; __device__ __forceinline__ unsigned cvt_pk_bf16(float lo, float hi) { const f32x2_t v = {lo, hi}; const bf16x2_t b = __builtin_convertvector(v, bf16x2_t); return __builtin_bit_cast(unsigned, b); }
; __device__ __forceinline__ float bfs2f(short b) { return __uint_as_float(((unsigned)(unsigned short)b) << 16); }
; __device__ __forceinline__ float tanh_fast(float x) { float e = __expf(2.f * x); return 1.f - 2.f / (e + 1.f); }
; __device__ __forceinline__ float gelu_tanh(float x) { return 0.5f * x * (1.f + tanh_fast(0.7978845608f * (x + 0.044715f * x * x * x))); }
; __device__ __forceinline__ void lru_pass(LAS unsigned char* L, int mode, const bf16_t* Z, const bf16_t* LWT, const float* conv_w, const float* conv_b, const float* b_a, const float* b_x, const float* lam,
;                          float* LSUM, const float* LCAR, bf16_t* Y) {
;     ...
;         if (mode == 1) {
;             { const int i = tid >> 3, sg = tid & 7; const size_t row = (size_t)b * S_ + seg * 64 + i;
;                 const bf16x8 gv = *(const bf16x8*)(Z + row * 2560 + 2048 + n * 64 + sg * 8); float y[8];
; #pragma unroll
;                 for (int e = 0; e < 8; ++e) { const int d = sg * 8 + e; y[e] = (UU[i * 65 + d] + UU[4160 + i * 65 + d]) * gelu_tanh(bfs2f(gv[e])); }
;                 u32x4 w; w.x = cvt_pk_bf16(y[0], y[1]); w.y = cvt_pk_bf16(y[2], y[3]); w.z = cvt_pk_bf16(y[4], y[5]); w.w = cvt_pk_bf16(y[6], y[7]);
;                 *(u32x4*)(Y + row * 1024 + 512 + n * 64 + sg * 8) = w; }
;             __syncthreads();
	v_pk_add_f32 v[16:17], v[16:17], v[18:19]
	v_pk_mul_f32 v[18:19], v[12:13], 0.5 op_sel_hi:[1,0]
	v_fmac_f32_e32 v13, v4, v13
	v_mul_f32_e32 v4, 0x3f4c422a, v13
	v_add_f32_e32 v4, v4, v4
	v_mul_f32_e32 v4, 0x3fb8aa3b, v4
	v_exp_f32_e32 v15, v4
	v_lshl_add_u64 v[2:3], s[2:3], 0, v[2:3]
	v_lshl_add_u64 v[2:3], v[2:3], 0, v[8:9]
	v_lshl_add_u64 v[2:3], v[2:3], 0, v[44:45]
	v_pk_add_f32 v[12:13], v[14:15], 1.0 op_sel_hi:[1,0]
	s_nop 0
	v_div_scale_f32 v4, s[4:5], v13, v13, 2.0
	v_rcp_f32_e32 v14, v4
	s_nop 0
	v_fma_f32 v15, -v4, v14, 1.0
	v_fmac_f32_e32 v14, v15, v14
	v_div_scale_f32 v15, vcc, 2.0, v13, 2.0
	v_mul_f32_e32 v20, v15, v14
	v_fma_f32 v21, -v4, v20, v15
	v_fmac_f32_e32 v20, v21, v14
	v_fma_f32 v4, -v4, v20, v15
	v_div_fmas_f32 v4, v4, v14, v20
	v_div_fixup_f32 v13, v4, v13, 2.0
	v_div_scale_f32 v4, s[4:5], v12, v12, 2.0
	v_rcp_f32_e32 v14, v4
	s_nop 0
	v_fma_f32 v15, -v4, v14, 1.0
	v_fmac_f32_e32 v14, v15, v14
	v_div_scale_f32 v15, vcc, 2.0, v12, 2.0
	v_mul_f32_e32 v20, v15, v14
	v_fma_f32 v21, -v4, v20, v15
	v_fmac_f32_e32 v20, v21, v14
	v_fma_f32 v4, -v4, v20, v15
	v_div_fmas_f32 v4, v4, v14, v20
	v_lshlrev_b32_e32 v14, 16, v5
	v_div_fixup_f32 v12, v4, v12, 2.0
	v_mul_f32_e32 v4, 0x3d372713, v14
	v_pk_add_f32 v[12:13], v[12:13], 1.0 op_sel_hi:[1,0] neg_lo:[1,0] neg_hi:[1,0]
	v_and_b32_e32 v15, 0xffff0000, v5
	v_mul_f32_e32 v4, v4, v14
	v_mov_b32_e32 v5, v14
	v_pk_add_f32 v[12:13], v[12:13], 1.0 op_sel_hi:[1,0]
	v_fmac_f32_e32 v5, v4, v5
	v_pk_mul_f32 v[12:13], v[18:19], v[12:13]
	v_mul_f32_e32 v4, 0x3f4c422a, v5
	v_add_u32_e32 v5, 0x4118, v242
	v_pk_mul_f32 v[12:13], v[16:17], v[12:13]
	ds_read2_b32 v[16:17], v242 offset0:6 offset1:7
	ds_read2_b32 v[18:19], v5 offset1:1
	v_mul_f32_e32 v5, 0x3d372713, v15
	v_mul_f32_e32 v5, v5, v15
	v_add_f32_e32 v4, v4, v4
	v_mul_f32_e32 v4, 0x3fb8aa3b, v4
	s_waitcnt lgkmcnt(0)
	v_pk_add_f32 v[16:17], v[16:17], v[18:19]
	v_pk_mul_f32 v[18:19], v[14:15], 0.5 op_sel_hi:[1,0]
	v_fmac_f32_e32 v15, v5, v15
	v_mul_f32_e32 v5, 0x3f4c422a, v15
	v_add_f32_e32 v5, v5, v5
	v_mul_f32_e32 v5, 0x3fb8aa3b, v5
	v_exp_f32_e32 v4, v4
	v_exp_f32_e32 v5, v5
	v_cvt_pk_bf16_f32 v12, v12, v13
	v_pk_add_f32 v[4:5], v[4:5], 1.0 op_sel_hi:[1,0]
	s_nop 0
	v_div_scale_f32 v14, s[4:5], v5, v5, 2.0
	v_rcp_f32_e32 v15, v14
	s_nop 0
	v_fma_f32 v20, -v14, v15, 1.0
	v_fmac_f32_e32 v15, v20, v15
	v_div_scale_f32 v20, vcc, 2.0, v5, 2.0
	v_mul_f32_e32 v21, v20, v15
	v_fma_f32 v22, -v14, v21, v20
	v_fmac_f32_e32 v21, v22, v15
	v_fma_f32 v14, -v14, v21, v20
	v_div_fmas_f32 v14, v14, v15, v21
	v_div_fixup_f32 v5, v14, v5, 2.0
	v_div_scale_f32 v14, s[4:5], v4, v4, 2.0
	v_rcp_f32_e32 v15, v14
	s_nop 0
	v_fma_f32 v20, -v14, v15, 1.0
	v_fmac_f32_e32 v15, v20, v15
	v_div_scale_f32 v20, vcc, 2.0, v4, 2.0
	v_mul_f32_e32 v21, v20, v15
	v_fma_f32 v22, -v14, v21, v20
	v_fmac_f32_e32 v21, v22, v15
	v_fma_f32 v14, -v14, v21, v20
	v_div_fmas_f32 v14, v14, v15, v21
	v_div_fixup_f32 v4, v14, v4, 2.0
	v_pk_add_f32 v[4:5], v[4:5], 1.0 op_sel_hi:[1,0] neg_lo:[1,0] neg_hi:[1,0]
	s_nop 0
	v_pk_add_f32 v[4:5], v[4:5], 1.0 op_sel_hi:[1,0]
	s_nop 0
	v_pk_mul_f32 v[4:5], v[18:19], v[4:5]
	s_nop 0
	v_pk_mul_f32 v[4:5], v[16:17], v[4:5]
	s_nop 0
	v_cvt_pk_bf16_f32 v13, v4, v5
	global_store_dwordx4 v[2:3], v[10:13], off offset:1024
	s_barrier
	s_branch .LBB0_590
